# short scan chains all on workgroups 256..383 (beside the RWKV long chains); 384..511 start on the queue at once
# speedup vs baseline: 1.0031x; 1.0031x over previous
; __device__ __forceinline__ void phase_scan(KP p, int l, unsigned char* smem) {
;     ...
;     const int NLONG = 256, NT_RS = 2048, NT_DS = 2048;
;     const int G = gridDim.x, bid = blockIdx.x;
;     const bool split = G >= 2 * NLONG;
;     if (split && bid < NLONG) {
;         if (bid < 128) rwkv_scan_task(p, l, false, bid >> 4, (bid >> 1) & 7, bid & 1, (float*)smem);
;         else { const int u = bid - 128; delta_scan_task(p, l, false, u >> 4, (u >> 2) & 3, u & 3, (float*)smem); }
;     } else {
;         const int first = split ? bid - NLONG : bid, stride = split ? G - NLONG : G;
;         const int total = (split ? 0 : NLONG) + NT_RS + NT_DS;
;         for (int t = first; t < total; t += stride) {
.LBB0_18:
	s_cmpk_gt_i32 s62, 0x1ff
	s_cselect_b64 s[6:7], -1, 0
	s_movk_i32 s27, 0x1000
	s_and_b64 s[6:7], s[6:7], exec
	s_cselect_b32 s11, s27, 0x1100
	s_add_i32 s3, s62, 0xffffff00
	s_cmpk_gt_i32 s62, 0x1ff
	s_cselect_b64 s[6:7], -1, 0
	s_and_b64 s[6:7], s[6:7], exec
	s_cselect_b32 s12, s3, s62
	s_add_i32 s10, s74, 0xffffff00
	s_cmpk_gt_i32 s62, 0x1ff
	s_cselect_b64 s[6:7], -1, 0
	s_and_b64 s[8:9], s[6:7], exec
	s_cselect_b32 s13, s10, s74
	s_cmp_lg_u32 s62, 0x200
	s_cbranch_scc1 .Lshort_done
	s_movk_i32 s12, 0x80
	s_cmpk_lt_i32 s74, 0x180
	s_cselect_b32 s13, s13, s11
.Lshort_done:
	s_cmpk_lt_i32 s74, 0x1100
	s_cselect_b64 s[8:9], -1, 0
	v_writelane_b32 v233, s8, 2
	s_cmpk_lt_i32 s74, 0x100
	s_mov_b32 s87, 0
	v_writelane_b32 v233, s9, 3
	s_cselect_b64 s[8:9], -1, 0
	s_cmpk_gt_i32 s74, 0x21f
	s_cselect_b64 s[14:15], -1, 0
	v_writelane_b32 v233, s14, 4
	s_lshl_b32 s48, s62, 2
	s_mov_b32 s75, s87
	v_writelane_b32 v233, s15, 5
	s_lshl_b32 s14, s74, 2
	s_cmpk_lt_i32 s62, 0x200
	s_cselect_b64 s[16:17], -1, 0
	v_writelane_b32 v233, s16, 6
	s_mul_i32 s3, s63, s62
	s_mov_b32 s63, s87
	v_writelane_b32 v233, s17, 7
	v_writelane_b32 v233, s8, 8
	s_and_b64 s[6:7], s[8:9], s[6:7]
	s_xor_b64 s[6:7], s[6:7], -1
	v_writelane_b32 v233, s9, 9
	v_writelane_b32 v233, s6, 10
	s_cmp_lt_i32 s13, s11
	s_mov_b32 s17, s87
	v_writelane_b32 v233, s7, 11
	v_writelane_b32 v233, s11, 12
	s_cselect_b64 s[6:7], -1, 0
	s_cmpk_lt_i32 s74, 0x80
	v_writelane_b32 v233, s6, 13
	s_cselect_b64 s[50:51], -1, 0
	s_cmpk_gt_i32 s74, 0x7f
	v_writelane_b32 v233, s7, 14
	s_cselect_b64 s[6:7], -1, 0
	v_writelane_b32 v233, s6, 15
	s_lshl_b32 s8, s74, 5
	s_and_b32 s9, s8, 0x60
	v_writelane_b32 v233, s7, 16
	s_add_i32 s6, s74, 0xffffff80
	s_lshr_b32 s7, s6, 4
	s_bfe_u32 s6, s74, 0x20002
	s_lshl_b32 s16, s7, 11
	s_lshl_b32 s7, s7, 2
	v_writelane_b32 v233, s9, 17
	s_or_b32 s7, s7, s6
	v_writelane_b32 v233, s7, 18
	s_lshl_b32 s7, s6, 7
	v_writelane_b32 v233, s7, 19
	s_ashr_i32 s9, s74, 4
	s_bfe_u32 s7, s74, 0x30001
	s_and_b32 s8, s8, 32
	s_lshl_b32 s10, s9, 3
	v_writelane_b32 v233, s8, 20
	s_lshl_b32 s8, s7, 6
	s_lshl_b32 s18, s6, 3
	s_lshl_b32 s20, s9, 11
	v_writelane_b32 v233, s8, 21
	s_or_b32 s8, s10, s7
	s_cmpk_lt_i32 s74, 0x880
	v_writelane_b32 v233, s8, 22
	s_cselect_b64 s[8:9], -1, 0
	v_writelane_b32 v233, s8, 23
	s_cmpk_lt_i32 s74, 0x13a8
	s_mov_b32 s19, s87
	v_writelane_b32 v233, s9, 24
	s_cselect_b64 s[8:9], -1, 0
	v_writelane_b32 v233, s8, 25
	s_lshl_b64 s[70:71], s[62:63], 8
	v_mov_b32_e32 v13, 0
	v_writelane_b32 v233, s9, 26
	s_lshl_b64 s[8:9], s[74:75], 8
	v_writelane_b32 v233, s8, 27
	v_writelane_b32 v230, s50, 0
	v_mov_b32_e32 v194, 0x3727c5ac
	v_writelane_b32 v233, s9, 28
	s_ashr_i32 s8, s74, 31
	s_lshr_b32 s9, s8, 28
	s_add_i32 s9, s74, s9
	s_and_b32 s10, s9, 0x3fffff0
	s_sub_i32 s10, s74, s10
	s_lshl_b32 s10, s10, 6
	s_lshl_b32 s9, s9, 2
	v_writelane_b32 v233, s10, 29
	s_and_b32 s10, s9, 0xffffffc0
	s_cmp_gt_i32 s10, -1
	v_writelane_b32 v233, s10, 30
	s_cselect_b64 s[22:23], -1, 0
	v_writelane_b32 v233, s22, 31
	s_cmpk_lt_i32 s74, 0x400
	v_writelane_b32 v230, s51, 1
	v_writelane_b32 v233, s23, 32
	s_cselect_b64 s[22:23], -1, 0
	v_writelane_b32 v233, s22, 33
	s_cmpk_lt_i32 s74, 0x200
	v_mov_b32_e32 v195, 1
	v_writelane_b32 v233, s23, 34
	s_cselect_b64 s[22:23], -1, 0
	s_lshr_b32 s8, s8, 27
	s_add_i32 s8, s74, s8
	s_and_b32 s9, s8, 0x3ffffe0
	v_writelane_b32 v233, s22, 35
	s_sub_i32 s9, s74, s9
	s_lshl_b32 s8, s8, 1
	v_writelane_b32 v233, s23, 36
	s_lshl_b32 s9, s9, 6
	s_andn2_b32 s8, s8, 63
	v_writelane_b32 v233, s9, 37
	s_cmp_gt_i32 s8, -1
	v_writelane_b32 v233, s8, 38
	s_cselect_b64 s[8:9], -1, 0
	v_writelane_b32 v233, s8, 39
	s_cmpk_lt_i32 s74, 0x4a0
	v_mov_b32_e32 v196, 13
	v_writelane_b32 v233, s9, 40
	s_cselect_b64 s[8:9], -1, 0
	v_writelane_b32 v233, s8, 41
	s_cmpk_gt_u32 s10, 0x11ff
	v_mov_b32_e32 v197, 2
	v_writelane_b32 v233, s9, 42
	s_cselect_b64 s[8:9], -1, 0
	v_writelane_b32 v233, s8, 43
	s_cmpk_lt_i32 s74, 0x1c0
	v_mov_b32_e32 v198, 4
	v_writelane_b32 v233, s9, 44
	s_cselect_b64 s[8:9], -1, 0
	v_writelane_b32 v233, s8, 45
	v_mov_b32_e32 v150, 0x358637bd
	v_mov_b32_e32 v151, 0x3a27c5ac
	v_writelane_b32 v233, s9, 46
	s_mul_hi_i32 s8, s74, 0x92492493
	s_add_i32 s8, s8, s74
	s_lshr_b32 s9, s8, 31
	s_ashr_i32 s8, s8, 4
	s_add_i32 s8, s8, s9
	s_mul_i32 s9, s8, 28
	s_sub_i32 s9, s74, s9
	s_lshl_b32 s9, s9, 6
	s_lshl_b32 s8, s8, 6
	v_writelane_b32 v233, s9, 47
	s_cmp_gt_i32 s8, -1
	v_writelane_b32 v233, s8, 48
	s_cselect_b64 s[8:9], -1, 0
	v_writelane_b32 v233, s8, 49
	s_cmp_lt_i32 s74, 4
	s_cselect_b64 s[52:53], -1, 0
	v_writelane_b32 v233, s9, 50
	s_lshr_b32 s8, s74, 31
	s_add_i32 s8, s74, s8
	s_and_b32 s9, s8, 0x3fffffe
	s_sub_i32 s9, s74, s9
	s_lshl_b32 s8, s8, 5
	s_lshl_b32 s9, s9, 6
	s_andn2_b32 s8, s8, 63
	v_writelane_b32 v233, s9, 51
	s_cmp_gt_i32 s8, -1
	v_writelane_b32 v233, s8, 52
	s_cselect_b64 s[8:9], -1, 0
	v_writelane_b32 v233, s8, 53
	s_cmp_lt_i32 s74, 8
	v_writelane_b32 v230, s52, 2
	v_writelane_b32 v233, s9, 54
	s_cselect_b64 s[8:9], -1, 0
	s_lshl_b32 s39, s74, 6
	v_writelane_b32 v233, s8, 55
	s_cmp_gt_i32 s39, -1
	v_writelane_b32 v230, s53, 3
	v_writelane_b32 v233, s9, 56
	s_cselect_b64 s[8:9], -1, 0
	v_writelane_b32 v233, s8, 57
	s_cmp_lt_i32 s74, 16
	v_writelane_b32 v230, s39, 4
	v_writelane_b32 v233, s9, 58
	s_cselect_b64 s[8:9], -1, 0
	v_writelane_b32 v233, s8, 59
	v_mov_b32_e32 v199, 0x800000
	v_mov_b32_e32 v200, 0x3fc7
	v_writelane_b32 v233, s9, 60
	s_add_u32 s8, s0, 0x28cf0200
	s_addc_u32 s9, s1, 0
	s_add_u32 s44, s0, 0x28cf0400
	s_addc_u32 s45, s1, 0
	s_add_u32 s54, s0, 0x28cf0500
	s_addc_u32 s55, s1, 0
	s_add_u32 s56, s0, 0x28cf0600
; __device__ __forceinline__ unsigned xb_ld(unsigned* p)              { return __hip_atomic_load(p, __ATOMIC_RELAXED, __HIP_MEMORY_SCOPE_AGENT); }
; __device__ __forceinline__ unsigned xb_add(unsigned* p, unsigned v) { return __hip_atomic_fetch_add(p, v, __ATOMIC_RELAXED, __HIP_MEMORY_SCOPE_AGENT); }
; __device__ __forceinline__ void phase_gemm_resid(const bf16_t* A, int lda, int K, const bf16_t* W, const float* X, float* Y, float scale, bf16_t* sm) {
;     const int G = gridDim.x, NTILES = 136 * 8;
;     const int nfull = (NTILES / G) * G;
; __device__ __forceinline__ void xcd_barrier_complete(unsigned* bar, unsigned x, unsigned& nloc, unsigned& nx) {
;     const unsigned G = gridDim.x * gridDim.y * gridDim.z;
;     unsigned sum, cnt, mine, sp = 0u;
;     for (;;) {
;         sum = 0u; cnt = 0u; mine = 0u;
; #pragma unroll
;         for (unsigned j = 0; j < 16; ++j) { const unsigned c = xb_ld(&bar[XB_XCNT(j)]); sum += c; cnt += (c > 0u) ? 1u : 0u; mine = (j == x) ? c : mine; }
;         if (sum == G) break;
;         __builtin_amdgcn_s_sleep(1);
;         if ((++sp & 255u) == 0u) { if (xb_ld(&bar[XB_TMO])) break; if (sp > XB_SPIN_CAP) { atomicAdd(&bar[XB_TMO], 1u); break; } }
;     }
;     nloc = mine > 0u ? mine : 1u; nx = cnt > 0u ? cnt : 1u;
; }
; __device__ __forceinline__ void xcd_barrier(const XcdBarrier& b) {
;     asm volatile("s_waitcnt vmcnt(0)" ::: "memory");
;     __syncthreads();
;     if (threadIdx.x == 0) {
;         unsigned* bar = b.bar;
;         __builtin_amdgcn_s_waitcnt(0);
;         unsigned nloc = b.st[0], nx = b.st[1];
;         if (nloc == 0u) { xcd_barrier_complete(bar, b.x, nloc, nx); b.st[0] = nloc; b.st[1] = nx; }
;         const unsigned old = xb_add(&bar[XB_XSUB(b.x)], 1u);
;         const unsigned gen = old / nloc;
;         if (old + 1u == (gen + 1u) * nloc) {
;             __builtin_amdgcn_fence(__ATOMIC_RELEASE, "agent");
;             asm volatile("s_waitcnt vmcnt(0)" ::: "memory");
;             const unsigned og = xb_add(&bar[XB_TOP], 1u);
;             const unsigned tg = og / nx;
;             if (og + 1u == (tg + 1u) * nx) xb_add(&bar[XB_TOPGEN], 1u);
;             else XB_SPIN(xb_ld(&bar[XB_TOPGEN]) == tg, bar);
;             __builtin_amdgcn_fence(__ATOMIC_ACQUIRE, "agent");
;             xb_add(&bar[XB_XGEN(b.x)], 1u);
	s_addc_u32 s57, s1, 0
	s_add_u32 s58, s0, 0x28cf0700
	s_addc_u32 s59, s1, 0
	s_add_u32 s80, s0, 0x28cf0800
	s_addc_u32 s81, s1, 0
	s_add_u32 s82, s0, 0x28cf0900
	s_addc_u32 s83, s1, 0
	s_add_u32 s84, s0, 0x28cf0a00
	s_addc_u32 s85, s1, 0
	s_add_u32 s90, s0, 0x28cf0b00
	v_writelane_b32 v233, s8, 61
	s_addc_u32 s91, s1, 0
	v_writelane_b32 v230, s44, 5
	v_writelane_b32 v233, s9, 62
	s_add_u32 s8, s0, 0x28cf0c00
	s_addc_u32 s9, s1, 0
	v_writelane_b32 v233, s8, 63
	v_writelane_b32 v230, s45, 6
	v_writelane_b32 v230, s54, 7
	v_writelane_b32 v232, s9, 0
	s_add_u32 s8, s0, 0x28cf0d00
	s_addc_u32 s9, s1, 0
	v_writelane_b32 v232, s8, 1
	v_writelane_b32 v230, s55, 8
	v_writelane_b32 v230, s56, 9
	v_writelane_b32 v232, s9, 2
	s_add_u32 s8, s0, 0x28cf0e00
	s_addc_u32 s9, s1, 0
	v_writelane_b32 v232, s8, 3
	v_writelane_b32 v230, s57, 10
	v_writelane_b32 v230, s58, 11
	v_writelane_b32 v232, s9, 4
	s_add_u32 s8, s0, 0x28cf0f00
	s_addc_u32 s9, s1, 0
	v_writelane_b32 v232, s8, 5
	v_writelane_b32 v230, s59, 12
	v_writelane_b32 v230, s80, 13
	v_writelane_b32 v232, s9, 6
	s_add_u32 s8, s0, 0x28cf1000
	s_addc_u32 s9, s1, 0
	v_writelane_b32 v232, s8, 7
	v_writelane_b32 v230, s81, 14
	v_writelane_b32 v230, s82, 15
	v_writelane_b32 v232, s9, 8
	s_add_u32 s8, s0, 0x28cf1100
	s_addc_u32 s9, s1, 0
	v_writelane_b32 v232, s8, 9
	v_writelane_b32 v230, s83, 16
	v_writelane_b32 v230, s84, 17
	v_writelane_b32 v232, s9, 10
	s_add_u32 s8, s0, 0x28cf1200
	s_addc_u32 s9, s1, 0
	v_writelane_b32 v232, s8, 11
	v_writelane_b32 v230, s85, 18
	v_mov_b32_e32 v201, 0x7ff
	v_writelane_b32 v232, s9, 12
	s_add_u32 s8, s0, 0x28cf1300
	s_addc_u32 s9, s1, 0
	v_writelane_b32 v232, s8, 13
	s_cmp_eq_u32 s2, 15
	v_mov_b32_e32 v202, 0x3fc5
	v_writelane_b32 v232, s9, 14
	s_cselect_b64 s[8:9], -1, 0
	v_writelane_b32 v232, s8, 15
	s_cmp_eq_u32 s2, 14
	v_mov_b32_e32 v203, 0x41b17218
	v_writelane_b32 v232, s9, 16
	s_cselect_b64 s[8:9], -1, 0
	v_writelane_b32 v232, s8, 17
	s_cmp_eq_u32 s2, 13
	v_mov_b32_e32 v204, 0x3000
	v_writelane_b32 v232, s9, 18
	s_cselect_b64 s[8:9], -1, 0
	v_writelane_b32 v232, s8, 19
	s_cmp_eq_u32 s2, 12
	v_mov_b32_e32 v205, 0x1800
	v_writelane_b32 v232, s9, 20
	s_cselect_b64 s[8:9], -1, 0
	v_writelane_b32 v232, s8, 21
	s_cmp_eq_u32 s2, 11
	v_mov_b32_e32 v206, 0xfffff800
	v_writelane_b32 v232, s9, 22
	s_cselect_b64 s[8:9], -1, 0
	v_writelane_b32 v232, s8, 23
	s_cmp_eq_u32 s2, 10
	v_mov_b32_e32 v207, 0x7ffff800
	v_writelane_b32 v232, s9, 24
	s_cselect_b64 s[8:9], -1, 0
	v_writelane_b32 v232, s8, 25
	s_cmp_eq_u32 s2, 9
	s_movk_i32 s29, 0x3000
	v_writelane_b32 v232, s9, 26
	s_cselect_b64 s[8:9], -1, 0
	v_writelane_b32 v232, s8, 27
	s_cmp_eq_u32 s2, 8
	s_movk_i32 s69, 0xf000
	v_writelane_b32 v232, s9, 28
	s_cselect_b64 s[8:9], -1, 0
	v_writelane_b32 v232, s8, 29
	s_cmp_eq_u32 s2, 7
	s_mov_b32 s73, 0x30000
	v_writelane_b32 v232, s9, 30
	s_cselect_b64 s[8:9], -1, 0
	v_writelane_b32 v232, s8, 31
	s_cmp_eq_u32 s2, 6
	s_movk_i32 s89, 0xa0
	v_writelane_b32 v232, s9, 32
	s_cselect_b64 s[8:9], -1, 0
	v_writelane_b32 v232, s8, 33
	s_cmp_eq_u32 s2, 5
	s_movk_i32 s36, 0xe00
	v_writelane_b32 v232, s9, 34
	s_cselect_b64 s[8:9], -1, 0
	v_writelane_b32 v232, s8, 35
	s_cmp_eq_u32 s2, 4
	s_mov_b32 s37, 0x20000
	v_writelane_b32 v232, s9, 36
	s_cselect_b64 s[8:9], -1, 0
	v_writelane_b32 v232, s8, 37
	s_cmp_eq_u32 s2, 3
	s_mov_b32 s64, 0x5f30000
	v_writelane_b32 v232, s9, 38
	s_cselect_b64 s[8:9], -1, 0
	v_writelane_b32 v232, s8, 39
	s_cmp_eq_u32 s2, 2
	s_mov_b32 s65, 0x5f40000
	v_writelane_b32 v232, s9, 40
	s_cselect_b64 s[8:9], -1, 0
	v_writelane_b32 v232, s8, 41
	s_cmp_eq_u32 s2, 1
	s_mov_b32 s33, 0x5f50000
	v_writelane_b32 v232, s9, 42
	s_cselect_b64 s[8:9], -1, 0
	v_writelane_b32 v232, s8, 43
	s_cmp_eq_u32 s2, 0
	s_movk_i32 s92, 0x2500
	v_writelane_b32 v232, s9, 44
	s_cselect_b64 s[8:9], -1, 0
	s_lshl_b32 s2, s2, 8
	s_add_u32 s2, s4, s2
	v_writelane_b32 v232, s8, 45
	s_addc_u32 s4, s5, 0
	s_mov_b32 s93, 0x16260000
	v_writelane_b32 v232, s9, 46
	s_add_u32 s8, s2, 0x1400
	s_addc_u32 s9, s4, 0
	v_writelane_b32 v232, s8, 47
	s_mov_b32 s38, 0x1c000
	s_movk_i32 s66, 0x1800
	v_writelane_b32 v232, s9, 48
	s_add_u32 s8, s2, 0x2400
	s_addc_u32 s9, s4, 0
	v_writelane_b32 v232, s8, 49
	s_add_u32 s4, s0, 0x28cf3400
	s_addc_u32 s5, s1, 0
	v_writelane_b32 v232, s9, 50
	v_writelane_b32 v232, s4, 51
	s_add_u32 s0, s0, 0x28cf3500
	s_addc_u32 s1, s1, 0
	v_writelane_b32 v232, s5, 52
	v_writelane_b32 v232, s0, 53
	s_movk_i32 s72, 0x7fff
	s_mov_b32 s67, 0x3f317217
	v_writelane_b32 v232, s1, 54
	s_abs_i32 s0, s62
	v_cvt_f32_u32_e32 v0, s0
	s_sub_i32 s1, 0, s0
	s_movk_i32 s60, 0x4800
	s_mov_b32 s61, 0x26a68000
	v_rcp_iflag_f32_e32 v0, v0
	s_mov_b32 s68, 0x8820
	s_mov_b32 s88, 0x3fd744fd
	s_mov_b32 s26, 0x2b8cbccc
	v_mul_f32_e32 v0, 0x4f7ffffe, v0
	v_cvt_u32_f32_e32 v0, v0
	s_mov_b64 s[30:31], 0x800
	s_mov_b64 s[34:35], 0x400
	v_writelane_b32 v230, s90, 19
	v_readfirstlane_b32 s2, v0
	s_mul_i32 s1, s1, s2
	s_mul_hi_u32 s1, s2, s1
	s_add_i32 s2, s2, s1
	s_mul_hi_u32 s1, s2, 0x440
	s_mul_i32 s1, s1, s0
	s_sub_i32 s1, 0x440, s1
	s_sub_i32 s2, s1, s0
	s_cmp_ge_u32 s1, s0
	s_cselect_b32 s1, s2, s1
	s_sub_i32 s2, s1, s0
	s_cmp_ge_u32 s1, s0
	s_cselect_b32 s0, s2, s1
	s_load_dword s2, s[76:77], 0x148
	s_sub_i32 s1, 0x440, s0
	s_cmp_lt_i32 s74, s1
	s_cselect_b64 s[4:5], -1, 0
	v_writelane_b32 v232, s4, 55
	s_waitcnt lgkmcnt(0)
; #define LAS __attribute__((address_space(3)))
; __device__ __forceinline__ void phase_gemm_resid(const bf16_t* A, int lda, int K, const bf16_t* W, const float* X, float* Y, float scale, bf16_t* sm) {
;     const int G = gridDim.x, NTILES = 136 * 8;
;     const int nfull = (NTILES / G) * G;
;     for (int t = blockIdx.x; t < nfull; t += G) resid_tile<4>(t >> 3, (t & 7) * 128, A, lda, K, W, X, Y, scale, sm);
;     for (int u = blockIdx.x; u < 2 * (NTILES - nfull); u += G) {
;         const int t = nfull + (u >> 1);
;         resid_tile<2>(t >> 3, (t & 7) * 128 + (u & 1) * 64, A, lda, K, W, X, Y, scale, sm);
;     }
; __global__ void __launch_bounds__(256, 2) mega(Params p, int ph_lo, int ph_hi) {
;     ...
;     KP kp0 = (KP)__builtin_amdgcn_kernarg_segment_ptr();
;     XcdBarrier xb = xcd_barrier_post((unsigned*)(kp0->ws + OFF_BAR), (volatile LAS unsigned*)&xb_words);
;     if (ph_hi > 100000) grid.sync();
;     for (int ph = ph_lo; ph < ph_hi; ++ph) {
	s_mul_i32 s2, s3, s2
	s_lshl_b32 s0, s0, 1
	v_writelane_b32 v232, s5, 56
	v_writelane_b32 v232, s2, 57
	s_cmp_lt_i32 s74, s0
	v_writelane_b32 v232, s0, 58
	s_cselect_b64 s[2:3], -1, 0
	v_writelane_b32 v232, s2, 59
	s_lshl_b32 s0, s6, 9
	v_mbcnt_lo_u32_b32 v0, -1, 0
	v_writelane_b32 v232, s3, 60
	s_mov_b32 s2, s16
	v_writelane_b32 v232, s2, 61
	v_mbcnt_hi_u32_b32 v193, -1, v0
	s_movk_i32 s6, 0x4000
	v_writelane_b32 v232, s3, 62
	s_lshl_b64 s[2:3], s[16:17], 11
	s_or_b32 s0, s2, s0
	s_lshl_b32 s2, s74, 7
	v_writelane_b32 v232, s2, 63
	s_lshl_b32 s2, s62, 7
	v_writelane_b32 v231, s2, 0
	s_add_i32 s2, s13, 0xffffff80
	v_writelane_b32 v231, s2, 1
	v_writelane_b32 v231, s13, 2
	s_lshl_b32 s2, s13, 5
	v_writelane_b32 v231, s2, 3
	v_writelane_b32 v231, s12, 4
	s_lshl_b32 s2, s12, 5
	v_writelane_b32 v231, s2, 5
	s_add_u32 s0, s0, 0xa321800
	v_writelane_b32 v231, s0, 6
	s_addc_u32 s0, s3, 0
	v_writelane_b32 v231, s0, 7
	s_mov_b32 s2, s20
	s_ashr_i32 s21, s20, 31
	v_writelane_b32 v231, s2, 8
	s_lshl_b32 s0, s7, 8
	s_mov_b32 s7, 0x10000
	v_writelane_b32 v231, s3, 9
	s_lshl_b64 s[2:3], s[20:21], 11
	s_or_b32 s0, s2, s0
	s_add_u32 s0, s0, 0x8121800
	v_writelane_b32 v231, s0, 10
	s_addc_u32 s0, s3, 0
	v_writelane_b32 v231, s0, 11
	v_writelane_b32 v231, s18, 12
	s_mul_hi_u32 s3, s62, 0x300
	s_mul_i32 s2, s62, 0x300
	v_writelane_b32 v231, s19, 13
	v_writelane_b32 v231, s2, 14
	s_add_i32 s0, s14, 0x3000
	s_ashr_i32 s49, s48, 31
	v_writelane_b32 v231, s3, 15
	v_writelane_b32 v231, s0, 16
	s_add_i32 s0, s14, 0xfffff000
	v_writelane_b32 v231, s0, 17
	s_lshl_b32 s0, s74, 4
	s_or_b32 s2, s0, 3
	v_writelane_b32 v231, s2, 18
	s_lshl_b32 s2, s62, 4
	v_writelane_b32 v231, s2, 19
	s_or_b32 s2, s0, 2
	v_writelane_b32 v231, s2, 20
	s_or_b32 s2, s0, 1
	v_writelane_b32 v231, s2, 21
	s_add_i32 s2, s0, -1
	v_writelane_b32 v231, s2, 22
	s_add_i32 s2, s0, -2
	v_writelane_b32 v231, s2, 23
	v_writelane_b32 v231, s0, 24
	s_add_i32 s0, s0, -3
	v_writelane_b32 v231, s0, 25
	v_writelane_b32 v231, s14, 26
	s_add_i32 s0, s14, s48
	v_writelane_b32 v231, s0, 27
	s_lshl_b64 s[2:3], s[48:49], 11
	v_writelane_b32 v231, s2, 28
	s_lshl_b64 s[4:5], s[62:63], 14
	s_mov_b64 s[20:21], 0x2000
	v_writelane_b32 v231, s3, 29
	s_lshl_b64 s[2:3], s[48:49], 12
	v_writelane_b32 v231, s2, 30
	v_writelane_b32 v230, s91, 20
	s_nop 0
	v_writelane_b32 v231, s3, 31
	s_lshl_b64 s[2:3], s[74:75], 10
	v_writelane_b32 v231, s2, 32
	s_nop 1
	v_writelane_b32 v231, s3, 33
	s_lshl_b64 s[2:3], s[62:63], 12
	v_writelane_b32 v231, s2, 34
	s_nop 1
	v_writelane_b32 v231, s3, 35
	s_lshl_b64 s[2:3], s[62:63], 9
	v_writelane_b32 v231, s2, 36
	s_nop 1
	v_writelane_b32 v231, s3, 37
	s_lshl_b64 s[2:3], s[62:63], 13
	v_writelane_b32 v231, s2, 38
	s_nop 1
	v_writelane_b32 v231, s3, 39
	v_writelane_b32 v231, s4, 40
	s_lshl_b64 s[2:3], s[74:75], 12
	s_nop 0
	v_writelane_b32 v231, s5, 41
	s_lshl_b64 s[4:5], s[62:63], 11
	v_writelane_b32 v231, s4, 42
	s_nop 1
	v_writelane_b32 v231, s5, 43
	s_lshl_b64 s[4:5], s[62:63], 10
	v_writelane_b32 v231, s4, 44
	s_mov_b32 s63, 0x800000
	s_nop 0
	v_writelane_b32 v231, s5, 45
	s_lshl_b64 s[4:5], s[74:75], 11
	s_add_u32 s0, s2, 0xfc000000
	v_writelane_b32 v231, s0, 46
	s_addc_u32 s0, s3, -1
	v_writelane_b32 v231, s0, 47
	s_add_u32 s0, s4, 0x3320004
	v_writelane_b32 v231, s0, 48
	v_writelane_b32 v231, s4, 49
	s_addc_u32 s0, s5, 0
	s_nop 0
	v_writelane_b32 v231, s5, 50
	v_writelane_b32 v231, s0, 51
	s_or_b32 s0, s2, 8
	v_writelane_b32 v231, s0, 52
	v_writelane_b32 v231, s2, 53
	s_mov_b32 s0, s3
	s_mov_b64 s[4:5], 0x80
	v_writelane_b32 v231, s3, 54
	v_writelane_b32 v231, s0, 55
	s_mov_b32 s3, 0x7ffffc0
	s_mov_b32 s2, s74
	v_writelane_b32 v231, s2, 56
	s_mov_b32 s0, 0x5f20000
	s_nop 0
	v_writelane_b32 v231, s3, 57
	v_writelane_b32 v231, s76, 58
	s_nop 1
	v_writelane_b32 v231, s77, 59
	v_writelane_b32 v231, s78, 60
	s_nop 1
	v_writelane_b32 v231, s79, 61
	v_writelane_b32 v231, s48, 62
	s_nop 1
	v_writelane_b32 v231, s49, 63
	s_branch .LBB0_22
